# EpiGlu epilogue (GLU gate + residual): same permlane16_swap / dwordx4 scheme as EpiResid, hb and z loads 6 groups deep, sigmoid batched per 8 columns
# baseline (speedup 1.0000x reference)
.LBB0_803:
	s_lshl_b32 s2, s0, 8
	v_readlane_b32 s0, v251, 20
	v_readlane_b32 s1, v251, 21
	v_readlane_b32 s26, v251, 24
	v_readlane_b32 s27, v251, 25
	v_and_b32_e32 v148, 0x60, v145
	v_and_b32_e32 v149, 16, v209
	v_and_b32_e32 v150, 32, v209
	v_lshrrev_b32_e32 v150, 2, v150
	v_or3_b32 v148, v148, v149, v150
	v_lshl_or_b32 v148, s10, 8, v148
	v_add_u32_e32 v149, s2, v143
	v_lshlrev_b32_e32 v150, 11, v149
	v_lshl_add_u32 v136, v148, 1, v150
	v_xor_b32_e32 v137, 16, v209
	v_xor_b32_e32 v138, 32, v209
	v_lshlrev_b32_e32 v137, 2, v137
	v_lshlrev_b32_e32 v138, 2, v138
	s_add_u32 s28, s0, 0x0
	s_addc_u32 s29, s1, 0
	s_add_u32 s100, s26, 0x0
	s_addc_u32 s101, s27, 0
	global_load_dwordx4 v[160:163], v136, s[28:29]
	global_load_dwordx4 v[164:167], v136, s[100:101]
	s_add_u32 s28, s0, 0x0
	s_addc_u32 s29, s1, 0
	s_add_u32 s100, s26, 0x0
	s_addc_u32 s101, s27, 0
	global_load_dwordx4 v[174:177], v136, s[28:29] offset:256
	global_load_dwordx4 v[178:181], v136, s[100:101] offset:256
	s_add_u32 s28, s0, 0x8000
	s_addc_u32 s29, s1, 0
	s_add_u32 s100, s26, 0x8000
	s_addc_u32 s101, s27, 0
	global_load_dwordx4 v[182:185], v136, s[28:29]
	global_load_dwordx4 v[186:189], v136, s[100:101]
	s_add_u32 s28, s0, 0x8000
	s_addc_u32 s29, s1, 0
	s_add_u32 s100, s26, 0x8000
	s_addc_u32 s101, s27, 0
	global_load_dwordx4 v[190:193], v136, s[28:29] offset:256
	global_load_dwordx4 v[194:197], v136, s[100:101] offset:256
	s_add_u32 s28, s0, 0x10000
	s_addc_u32 s29, s1, 0
	s_add_u32 s100, s26, 0x10000
	s_addc_u32 s101, s27, 0
	global_load_dwordx4 v[198:201], v136, s[28:29]
	global_load_dwordx4 v[202:205], v136, s[100:101]
	s_add_u32 s28, s0, 0x10000
	s_addc_u32 s29, s1, 0
	s_add_u32 s100, s26, 0x10000
	s_addc_u32 s101, s27, 0
	global_load_dwordx4 v[222:225], v136, s[28:29] offset:256
	global_load_dwordx4 v[226:229], v136, s[100:101] offset:256
	s_waitcnt vmcnt(10)
	v_permlane16_swap_b32_e32 v126, v122
	v_permlane16_swap_b32_e32 v127, v123
	v_permlane16_swap_b32_e32 v128, v124
	v_permlane16_swap_b32_e32 v129, v125
	v_mul_f32_e32 v126, 0xbfb8aa3b, v126
	v_mul_f32_e32 v127, 0xbfb8aa3b, v127
	v_mul_f32_e32 v128, 0xbfb8aa3b, v128
	v_mul_f32_e32 v129, 0xbfb8aa3b, v129
	v_mul_f32_e32 v122, 0xbfb8aa3b, v122
	v_mul_f32_e32 v123, 0xbfb8aa3b, v123
	v_mul_f32_e32 v124, 0xbfb8aa3b, v124
	v_mul_f32_e32 v125, 0xbfb8aa3b, v125
	v_exp_f32_e32 v126, v126
	v_exp_f32_e32 v127, v127
	v_exp_f32_e32 v128, v128
	v_exp_f32_e32 v129, v129
	v_exp_f32_e32 v122, v122
	v_exp_f32_e32 v123, v123
	v_exp_f32_e32 v124, v124
	v_exp_f32_e32 v125, v125
	v_add_f32_e32 v126, 1.0, v126
	v_add_f32_e32 v127, 1.0, v127
	v_add_f32_e32 v128, 1.0, v128
	v_add_f32_e32 v129, 1.0, v129
	v_add_f32_e32 v122, 1.0, v122
	v_add_f32_e32 v123, 1.0, v123
	v_add_f32_e32 v124, 1.0, v124
	v_add_f32_e32 v125, 1.0, v125
	v_rcp_f32_e32 v126, v126
	v_rcp_f32_e32 v127, v127
	v_rcp_f32_e32 v128, v128
	v_rcp_f32_e32 v129, v129
	v_rcp_f32_e32 v122, v122
	v_rcp_f32_e32 v123, v123
	v_rcp_f32_e32 v124, v124
	v_rcp_f32_e32 v125, v125
	v_lshlrev_b32_e32 v148, 16, v160
	v_lshlrev_b32_e32 v149, 16, v164
	v_and_b32_e32 v150, 0xffff0000, v160
	v_and_b32_e32 v151, 0xffff0000, v164
	v_fma_f32 v126, v126, v149, v148
	v_fma_f32 v127, v127, v151, v150
	v_lshlrev_b32_e32 v152, 16, v161
	v_lshlrev_b32_e32 v153, 16, v165
	v_and_b32_e32 v154, 0xffff0000, v161
	v_and_b32_e32 v155, 0xffff0000, v165
	v_fma_f32 v128, v128, v153, v152
	v_fma_f32 v129, v129, v155, v154
	v_lshlrev_b32_e32 v148, 16, v162
	v_lshlrev_b32_e32 v149, 16, v166
	v_and_b32_e32 v150, 0xffff0000, v162
	v_and_b32_e32 v151, 0xffff0000, v166
	v_fma_f32 v122, v122, v149, v148
	v_fma_f32 v123, v123, v151, v150
	v_lshlrev_b32_e32 v152, 16, v163
	v_lshlrev_b32_e32 v153, 16, v167
	v_and_b32_e32 v154, 0xffff0000, v163
	v_and_b32_e32 v155, 0xffff0000, v167
	v_fma_f32 v124, v124, v153, v152
	v_fma_f32 v125, v125, v155, v154
	v_cvt_pk_bf16_f32 v160, v126, v127
	v_cvt_pk_bf16_f32 v161, v128, v129
	v_cvt_pk_bf16_f32 v162, v122, v123
	v_cvt_pk_bf16_f32 v163, v124, v125
	s_add_u32 s28, s0, 0x0
	s_addc_u32 s29, s1, 0
	global_store_dwordx4 v136, v[160:163], s[28:29]
	s_add_u32 s28, s0, 0x18000
	s_addc_u32 s29, s1, 0
	s_add_u32 s100, s26, 0x18000
	s_addc_u32 s101, s27, 0
	global_load_dwordx4 v[126:129], v136, s[28:29]
	global_load_dwordx4 v[122:125], v136, s[100:101]
	v_lshlrev_b32_e32 v148, 16, v160
	v_lshlrev_b32_e32 v149, 16, v161
	v_and_b32_e32 v150, 0xffff0000, v160
	v_and_b32_e32 v151, 0xffff0000, v161
	v_lshlrev_b32_e32 v152, 16, v162
	v_lshlrev_b32_e32 v153, 16, v163
	v_and_b32_e32 v154, 0xffff0000, v162
	v_and_b32_e32 v155, 0xffff0000, v163
	v_pk_mul_f32 v[150:151], v[150:151], v[150:151]
	v_pk_mul_f32 v[154:155], v[154:155], v[154:155]
	v_pk_fma_f32 v[148:149], v[148:149], v[148:149], v[150:151]
	v_pk_fma_f32 v[152:153], v[152:153], v[152:153], v[154:155]
	s_nop 0
	v_add_f32_e32 v148, v148, v149
	v_add_f32_e32 v152, v152, v153
	v_add_f32_e32 v156, v148, v152
	s_waitcnt vmcnt(11)
	v_permlane16_swap_b32_e32 v118, v114
	v_permlane16_swap_b32_e32 v119, v115
	v_permlane16_swap_b32_e32 v120, v116
	v_permlane16_swap_b32_e32 v121, v117
	v_mul_f32_e32 v118, 0xbfb8aa3b, v118
	v_mul_f32_e32 v119, 0xbfb8aa3b, v119
	v_mul_f32_e32 v120, 0xbfb8aa3b, v120
	v_mul_f32_e32 v121, 0xbfb8aa3b, v121
	v_mul_f32_e32 v114, 0xbfb8aa3b, v114
	v_mul_f32_e32 v115, 0xbfb8aa3b, v115
	v_mul_f32_e32 v116, 0xbfb8aa3b, v116
	v_mul_f32_e32 v117, 0xbfb8aa3b, v117
	v_exp_f32_e32 v118, v118
	v_exp_f32_e32 v119, v119
	v_exp_f32_e32 v120, v120
	v_exp_f32_e32 v121, v121
	v_exp_f32_e32 v114, v114
	v_exp_f32_e32 v115, v115
	v_exp_f32_e32 v116, v116
	v_exp_f32_e32 v117, v117
	v_add_f32_e32 v118, 1.0, v118
	v_add_f32_e32 v119, 1.0, v119
	v_add_f32_e32 v120, 1.0, v120
	v_add_f32_e32 v121, 1.0, v121
	v_add_f32_e32 v114, 1.0, v114
	v_add_f32_e32 v115, 1.0, v115
	v_add_f32_e32 v116, 1.0, v116
	v_add_f32_e32 v117, 1.0, v117
	v_rcp_f32_e32 v118, v118
	v_rcp_f32_e32 v119, v119
	v_rcp_f32_e32 v120, v120
	v_rcp_f32_e32 v121, v121
	v_rcp_f32_e32 v114, v114
	v_rcp_f32_e32 v115, v115
	v_rcp_f32_e32 v116, v116
	v_rcp_f32_e32 v117, v117
	v_lshlrev_b32_e32 v148, 16, v174
	v_lshlrev_b32_e32 v149, 16, v178
	v_and_b32_e32 v150, 0xffff0000, v174
	v_and_b32_e32 v151, 0xffff0000, v178
	v_fma_f32 v118, v118, v149, v148
	v_fma_f32 v119, v119, v151, v150
	v_lshlrev_b32_e32 v152, 16, v175
	v_lshlrev_b32_e32 v153, 16, v179
	v_and_b32_e32 v154, 0xffff0000, v175
	v_and_b32_e32 v155, 0xffff0000, v179
	v_fma_f32 v120, v120, v153, v152
	v_fma_f32 v121, v121, v155, v154
	v_lshlrev_b32_e32 v148, 16, v176
	v_lshlrev_b32_e32 v149, 16, v180
	v_and_b32_e32 v150, 0xffff0000, v176
	v_and_b32_e32 v151, 0xffff0000, v180
	v_fma_f32 v114, v114, v149, v148
	v_fma_f32 v115, v115, v151, v150
	v_lshlrev_b32_e32 v152, 16, v177
	v_lshlrev_b32_e32 v153, 16, v181
	v_and_b32_e32 v154, 0xffff0000, v177
	v_and_b32_e32 v155, 0xffff0000, v181
	v_fma_f32 v116, v116, v153, v152
	v_fma_f32 v117, v117, v155, v154
	v_cvt_pk_bf16_f32 v174, v118, v119
	v_cvt_pk_bf16_f32 v175, v120, v121
	v_cvt_pk_bf16_f32 v176, v114, v115
	v_cvt_pk_bf16_f32 v177, v116, v117
	s_add_u32 s28, s0, 0x0
	s_addc_u32 s29, s1, 0
	global_store_dwordx4 v136, v[174:177], s[28:29] offset:256
	s_add_u32 s28, s0, 0x18000
	s_addc_u32 s29, s1, 0
	s_add_u32 s100, s26, 0x18000
	s_addc_u32 s101, s27, 0
	global_load_dwordx4 v[118:121], v136, s[28:29] offset:256
	global_load_dwordx4 v[114:117], v136, s[100:101] offset:256
	v_lshlrev_b32_e32 v148, 16, v174
	v_lshlrev_b32_e32 v149, 16, v175
	v_and_b32_e32 v150, 0xffff0000, v174
	v_and_b32_e32 v151, 0xffff0000, v175
	v_lshlrev_b32_e32 v152, 16, v176
	v_lshlrev_b32_e32 v153, 16, v177
	v_and_b32_e32 v154, 0xffff0000, v176
	v_and_b32_e32 v155, 0xffff0000, v177
	v_pk_mul_f32 v[150:151], v[150:151], v[150:151]
	v_pk_mul_f32 v[154:155], v[154:155], v[154:155]
	v_pk_fma_f32 v[148:149], v[148:149], v[148:149], v[150:151]
	v_pk_fma_f32 v[152:153], v[152:153], v[152:153], v[154:155]
	s_nop 0
	v_add_f32_e32 v148, v148, v149
	v_add_f32_e32 v152, v152, v153
	v_add_f32_e32 v156, v156, v148
	v_add_f32_e32 v156, v156, v152
	s_waitcnt vmcnt(12)
	v_permlane16_swap_b32_e32 v110, v106
	v_permlane16_swap_b32_e32 v111, v107
	v_permlane16_swap_b32_e32 v112, v108
	v_permlane16_swap_b32_e32 v113, v109
	v_mul_f32_e32 v110, 0xbfb8aa3b, v110
	v_mul_f32_e32 v111, 0xbfb8aa3b, v111
	v_mul_f32_e32 v112, 0xbfb8aa3b, v112
	v_mul_f32_e32 v113, 0xbfb8aa3b, v113
	v_mul_f32_e32 v106, 0xbfb8aa3b, v106
	v_mul_f32_e32 v107, 0xbfb8aa3b, v107
	v_mul_f32_e32 v108, 0xbfb8aa3b, v108
	v_mul_f32_e32 v109, 0xbfb8aa3b, v109
	v_exp_f32_e32 v110, v110
	v_exp_f32_e32 v111, v111
	v_exp_f32_e32 v112, v112
	v_exp_f32_e32 v113, v113
	v_exp_f32_e32 v106, v106
	v_exp_f32_e32 v107, v107
	v_exp_f32_e32 v108, v108
	v_exp_f32_e32 v109, v109
	v_add_f32_e32 v110, 1.0, v110
	v_add_f32_e32 v111, 1.0, v111
	v_add_f32_e32 v112, 1.0, v112
	v_add_f32_e32 v113, 1.0, v113
	v_add_f32_e32 v106, 1.0, v106
	v_add_f32_e32 v107, 1.0, v107
	v_add_f32_e32 v108, 1.0, v108
	v_add_f32_e32 v109, 1.0, v109
	v_rcp_f32_e32 v110, v110
	v_rcp_f32_e32 v111, v111
	v_rcp_f32_e32 v112, v112
	v_rcp_f32_e32 v113, v113
	v_rcp_f32_e32 v106, v106
	v_rcp_f32_e32 v107, v107
	v_rcp_f32_e32 v108, v108
	v_rcp_f32_e32 v109, v109
	v_lshlrev_b32_e32 v148, 16, v182
	v_lshlrev_b32_e32 v149, 16, v186
	v_and_b32_e32 v150, 0xffff0000, v182
	v_and_b32_e32 v151, 0xffff0000, v186
	v_fma_f32 v110, v110, v149, v148
	v_fma_f32 v111, v111, v151, v150
	v_lshlrev_b32_e32 v152, 16, v183
	v_lshlrev_b32_e32 v153, 16, v187
	v_and_b32_e32 v154, 0xffff0000, v183
	v_and_b32_e32 v155, 0xffff0000, v187
	v_fma_f32 v112, v112, v153, v152
	v_fma_f32 v113, v113, v155, v154
	v_lshlrev_b32_e32 v148, 16, v184
	v_lshlrev_b32_e32 v149, 16, v188
	v_and_b32_e32 v150, 0xffff0000, v184
	v_and_b32_e32 v151, 0xffff0000, v188
	v_fma_f32 v106, v106, v149, v148
	v_fma_f32 v107, v107, v151, v150
	v_lshlrev_b32_e32 v152, 16, v185
	v_lshlrev_b32_e32 v153, 16, v189
	v_and_b32_e32 v154, 0xffff0000, v185
	v_and_b32_e32 v155, 0xffff0000, v189
	v_fma_f32 v108, v108, v153, v152
	v_fma_f32 v109, v109, v155, v154
	v_cvt_pk_bf16_f32 v182, v110, v111
	v_cvt_pk_bf16_f32 v183, v112, v113
	v_cvt_pk_bf16_f32 v184, v106, v107
	v_cvt_pk_bf16_f32 v185, v108, v109
	s_add_u32 s28, s0, 0x8000
	s_addc_u32 s29, s1, 0
	global_store_dwordx4 v136, v[182:185], s[28:29]
	s_add_u32 s28, s0, 0x40000
	s_addc_u32 s29, s1, 0
	s_add_u32 s100, s26, 0x40000
	s_addc_u32 s101, s27, 0
	global_load_dwordx4 v[110:113], v136, s[28:29]
	global_load_dwordx4 v[106:109], v136, s[100:101]
	v_lshlrev_b32_e32 v148, 16, v182
	v_lshlrev_b32_e32 v149, 16, v183
	v_and_b32_e32 v150, 0xffff0000, v182
	v_and_b32_e32 v151, 0xffff0000, v183
	v_lshlrev_b32_e32 v152, 16, v184
	v_lshlrev_b32_e32 v153, 16, v185
	v_and_b32_e32 v154, 0xffff0000, v184
	v_and_b32_e32 v155, 0xffff0000, v185
	v_pk_mul_f32 v[150:151], v[150:151], v[150:151]
	v_pk_mul_f32 v[154:155], v[154:155], v[154:155]
	v_pk_fma_f32 v[148:149], v[148:149], v[148:149], v[150:151]
	v_pk_fma_f32 v[152:153], v[152:153], v[152:153], v[154:155]
	s_nop 0
	v_add_f32_e32 v148, v148, v149
	v_add_f32_e32 v152, v152, v153
	v_add_f32_e32 v157, v148, v152
	s_waitcnt vmcnt(13)
	v_permlane16_swap_b32_e32 v102, v98
	v_permlane16_swap_b32_e32 v103, v99
	v_permlane16_swap_b32_e32 v104, v100
	v_permlane16_swap_b32_e32 v105, v101
	v_mul_f32_e32 v102, 0xbfb8aa3b, v102
	v_mul_f32_e32 v103, 0xbfb8aa3b, v103
	v_mul_f32_e32 v104, 0xbfb8aa3b, v104
	v_mul_f32_e32 v105, 0xbfb8aa3b, v105
	v_mul_f32_e32 v98, 0xbfb8aa3b, v98
	v_mul_f32_e32 v99, 0xbfb8aa3b, v99
	v_mul_f32_e32 v100, 0xbfb8aa3b, v100
	v_mul_f32_e32 v101, 0xbfb8aa3b, v101
	v_exp_f32_e32 v102, v102
	v_exp_f32_e32 v103, v103
	v_exp_f32_e32 v104, v104
	v_exp_f32_e32 v105, v105
	v_exp_f32_e32 v98, v98
	v_exp_f32_e32 v99, v99
	v_exp_f32_e32 v100, v100
	v_exp_f32_e32 v101, v101
	v_add_f32_e32 v102, 1.0, v102
	v_add_f32_e32 v103, 1.0, v103
	v_add_f32_e32 v104, 1.0, v104
	v_add_f32_e32 v105, 1.0, v105
	v_add_f32_e32 v98, 1.0, v98
	v_add_f32_e32 v99, 1.0, v99
	v_add_f32_e32 v100, 1.0, v100
	v_add_f32_e32 v101, 1.0, v101
	v_rcp_f32_e32 v102, v102
	v_rcp_f32_e32 v103, v103
	v_rcp_f32_e32 v104, v104
	v_rcp_f32_e32 v105, v105
	v_rcp_f32_e32 v98, v98
	v_rcp_f32_e32 v99, v99
	v_rcp_f32_e32 v100, v100
	v_rcp_f32_e32 v101, v101
	v_lshlrev_b32_e32 v148, 16, v190
	v_lshlrev_b32_e32 v149, 16, v194
	v_and_b32_e32 v150, 0xffff0000, v190
	v_and_b32_e32 v151, 0xffff0000, v194
	v_fma_f32 v102, v102, v149, v148
	v_fma_f32 v103, v103, v151, v150
	v_lshlrev_b32_e32 v152, 16, v191
	v_lshlrev_b32_e32 v153, 16, v195
	v_and_b32_e32 v154, 0xffff0000, v191
	v_and_b32_e32 v155, 0xffff0000, v195
	v_fma_f32 v104, v104, v153, v152
	v_fma_f32 v105, v105, v155, v154
	v_lshlrev_b32_e32 v148, 16, v192
	v_lshlrev_b32_e32 v149, 16, v196
	v_and_b32_e32 v150, 0xffff0000, v192
	v_and_b32_e32 v151, 0xffff0000, v196
	v_fma_f32 v98, v98, v149, v148
	v_fma_f32 v99, v99, v151, v150
	v_lshlrev_b32_e32 v152, 16, v193
	v_lshlrev_b32_e32 v153, 16, v197
	v_and_b32_e32 v154, 0xffff0000, v193
	v_and_b32_e32 v155, 0xffff0000, v197
	v_fma_f32 v100, v100, v153, v152
	v_fma_f32 v101, v101, v155, v154
	v_cvt_pk_bf16_f32 v190, v102, v103
	v_cvt_pk_bf16_f32 v191, v104, v105
	v_cvt_pk_bf16_f32 v192, v98, v99
	v_cvt_pk_bf16_f32 v193, v100, v101
	s_add_u32 s28, s0, 0x8000
	s_addc_u32 s29, s1, 0
	global_store_dwordx4 v136, v[190:193], s[28:29] offset:256
	s_add_u32 s28, s0, 0x40000
	s_addc_u32 s29, s1, 0
	s_add_u32 s100, s26, 0x40000
	s_addc_u32 s101, s27, 0
	global_load_dwordx4 v[102:105], v136, s[28:29] offset:256
	global_load_dwordx4 v[98:101], v136, s[100:101] offset:256
	v_lshlrev_b32_e32 v148, 16, v190
	v_lshlrev_b32_e32 v149, 16, v191
	v_and_b32_e32 v150, 0xffff0000, v190
	v_and_b32_e32 v151, 0xffff0000, v191
	v_lshlrev_b32_e32 v152, 16, v192
	v_lshlrev_b32_e32 v153, 16, v193
	v_and_b32_e32 v154, 0xffff0000, v192
	v_and_b32_e32 v155, 0xffff0000, v193
	v_pk_mul_f32 v[150:151], v[150:151], v[150:151]
	v_pk_mul_f32 v[154:155], v[154:155], v[154:155]
	v_pk_fma_f32 v[148:149], v[148:149], v[148:149], v[150:151]
	v_pk_fma_f32 v[152:153], v[152:153], v[152:153], v[154:155]
	s_nop 0
	v_add_f32_e32 v148, v148, v149
	v_add_f32_e32 v152, v152, v153
	v_add_f32_e32 v157, v157, v148
	v_add_f32_e32 v157, v157, v152
	s_waitcnt vmcnt(14)
	v_permlane16_swap_b32_e32 v92, v88
	v_permlane16_swap_b32_e32 v93, v89
	v_permlane16_swap_b32_e32 v94, v90
	v_permlane16_swap_b32_e32 v95, v91
	v_mul_f32_e32 v92, 0xbfb8aa3b, v92
	v_mul_f32_e32 v93, 0xbfb8aa3b, v93
	v_mul_f32_e32 v94, 0xbfb8aa3b, v94
	v_mul_f32_e32 v95, 0xbfb8aa3b, v95
	v_mul_f32_e32 v88, 0xbfb8aa3b, v88
	v_mul_f32_e32 v89, 0xbfb8aa3b, v89
	v_mul_f32_e32 v90, 0xbfb8aa3b, v90
	v_mul_f32_e32 v91, 0xbfb8aa3b, v91
	v_exp_f32_e32 v92, v92
	v_exp_f32_e32 v93, v93
	v_exp_f32_e32 v94, v94
	v_exp_f32_e32 v95, v95
	v_exp_f32_e32 v88, v88
	v_exp_f32_e32 v89, v89
	v_exp_f32_e32 v90, v90
	v_exp_f32_e32 v91, v91
	v_add_f32_e32 v92, 1.0, v92
	v_add_f32_e32 v93, 1.0, v93
	v_add_f32_e32 v94, 1.0, v94
	v_add_f32_e32 v95, 1.0, v95
	v_add_f32_e32 v88, 1.0, v88
	v_add_f32_e32 v89, 1.0, v89
	v_add_f32_e32 v90, 1.0, v90
	v_add_f32_e32 v91, 1.0, v91
	v_rcp_f32_e32 v92, v92
	v_rcp_f32_e32 v93, v93
	v_rcp_f32_e32 v94, v94
	v_rcp_f32_e32 v95, v95
	v_rcp_f32_e32 v88, v88
	v_rcp_f32_e32 v89, v89
	v_rcp_f32_e32 v90, v90
	v_rcp_f32_e32 v91, v91
	v_lshlrev_b32_e32 v148, 16, v198
	v_lshlrev_b32_e32 v149, 16, v202
	v_and_b32_e32 v150, 0xffff0000, v198
	v_and_b32_e32 v151, 0xffff0000, v202
	v_fma_f32 v92, v92, v149, v148
	v_fma_f32 v93, v93, v151, v150
	v_lshlrev_b32_e32 v152, 16, v199
	v_lshlrev_b32_e32 v153, 16, v203
	v_and_b32_e32 v154, 0xffff0000, v199
	v_and_b32_e32 v155, 0xffff0000, v203
	v_fma_f32 v94, v94, v153, v152
	v_fma_f32 v95, v95, v155, v154
	v_lshlrev_b32_e32 v148, 16, v200
	v_lshlrev_b32_e32 v149, 16, v204
	v_and_b32_e32 v150, 0xffff0000, v200
	v_and_b32_e32 v151, 0xffff0000, v204
	v_fma_f32 v88, v88, v149, v148
	v_fma_f32 v89, v89, v151, v150
	v_lshlrev_b32_e32 v152, 16, v201
	v_lshlrev_b32_e32 v153, 16, v205
	v_and_b32_e32 v154, 0xffff0000, v201
	v_and_b32_e32 v155, 0xffff0000, v205
	v_fma_f32 v90, v90, v153, v152
	v_fma_f32 v91, v91, v155, v154
	v_cvt_pk_bf16_f32 v198, v92, v93
	v_cvt_pk_bf16_f32 v199, v94, v95
	v_cvt_pk_bf16_f32 v200, v88, v89
	v_cvt_pk_bf16_f32 v201, v90, v91
	s_add_u32 s28, s0, 0x10000
	s_addc_u32 s29, s1, 0
	global_store_dwordx4 v136, v[198:201], s[28:29]
	s_add_u32 s28, s0, 0x48000
	s_addc_u32 s29, s1, 0
	s_add_u32 s100, s26, 0x48000
	s_addc_u32 s101, s27, 0
	global_load_dwordx4 v[92:95], v136, s[28:29]
	global_load_dwordx4 v[88:91], v136, s[100:101]
	v_lshlrev_b32_e32 v148, 16, v198
	v_lshlrev_b32_e32 v149, 16, v199
	v_and_b32_e32 v150, 0xffff0000, v198
	v_and_b32_e32 v151, 0xffff0000, v199
	v_lshlrev_b32_e32 v152, 16, v200
	v_lshlrev_b32_e32 v153, 16, v201
	v_and_b32_e32 v154, 0xffff0000, v200
	v_and_b32_e32 v155, 0xffff0000, v201
	v_pk_mul_f32 v[150:151], v[150:151], v[150:151]
	v_pk_mul_f32 v[154:155], v[154:155], v[154:155]
	v_pk_fma_f32 v[148:149], v[148:149], v[148:149], v[150:151]
	v_pk_fma_f32 v[152:153], v[152:153], v[152:153], v[154:155]
	s_nop 0
	v_add_f32_e32 v148, v148, v149
	v_add_f32_e32 v152, v152, v153
	v_add_f32_e32 v158, v148, v152
	s_waitcnt vmcnt(15)
	v_permlane16_swap_b32_e32 v84, v80
	v_permlane16_swap_b32_e32 v85, v81
	v_permlane16_swap_b32_e32 v86, v82
	v_permlane16_swap_b32_e32 v87, v83
	v_mul_f32_e32 v84, 0xbfb8aa3b, v84
	v_mul_f32_e32 v85, 0xbfb8aa3b, v85
	v_mul_f32_e32 v86, 0xbfb8aa3b, v86
	v_mul_f32_e32 v87, 0xbfb8aa3b, v87
	v_mul_f32_e32 v80, 0xbfb8aa3b, v80
	v_mul_f32_e32 v81, 0xbfb8aa3b, v81
	v_mul_f32_e32 v82, 0xbfb8aa3b, v82
	v_mul_f32_e32 v83, 0xbfb8aa3b, v83
	v_exp_f32_e32 v84, v84
	v_exp_f32_e32 v85, v85
	v_exp_f32_e32 v86, v86
	v_exp_f32_e32 v87, v87
	v_exp_f32_e32 v80, v80
	v_exp_f32_e32 v81, v81
	v_exp_f32_e32 v82, v82
	v_exp_f32_e32 v83, v83
	v_add_f32_e32 v84, 1.0, v84
	v_add_f32_e32 v85, 1.0, v85
	v_add_f32_e32 v86, 1.0, v86
	v_add_f32_e32 v87, 1.0, v87
	v_add_f32_e32 v80, 1.0, v80
	v_add_f32_e32 v81, 1.0, v81
	v_add_f32_e32 v82, 1.0, v82
	v_add_f32_e32 v83, 1.0, v83
	v_rcp_f32_e32 v84, v84
	v_rcp_f32_e32 v85, v85
	v_rcp_f32_e32 v86, v86
	v_rcp_f32_e32 v87, v87
	v_rcp_f32_e32 v80, v80
	v_rcp_f32_e32 v81, v81
	v_rcp_f32_e32 v82, v82
	v_rcp_f32_e32 v83, v83
	v_lshlrev_b32_e32 v148, 16, v222
	v_lshlrev_b32_e32 v149, 16, v226
	v_and_b32_e32 v150, 0xffff0000, v222
	v_and_b32_e32 v151, 0xffff0000, v226
	v_fma_f32 v84, v84, v149, v148
	v_fma_f32 v85, v85, v151, v150
	v_lshlrev_b32_e32 v152, 16, v223
	v_lshlrev_b32_e32 v153, 16, v227
	v_and_b32_e32 v154, 0xffff0000, v223
	v_and_b32_e32 v155, 0xffff0000, v227
	v_fma_f32 v86, v86, v153, v152
	v_fma_f32 v87, v87, v155, v154
	v_lshlrev_b32_e32 v148, 16, v224
	v_lshlrev_b32_e32 v149, 16, v228
	v_and_b32_e32 v150, 0xffff0000, v224
	v_and_b32_e32 v151, 0xffff0000, v228
	v_fma_f32 v80, v80, v149, v148
	v_fma_f32 v81, v81, v151, v150
	v_lshlrev_b32_e32 v152, 16, v225
	v_lshlrev_b32_e32 v153, 16, v229
	v_and_b32_e32 v154, 0xffff0000, v225
	v_and_b32_e32 v155, 0xffff0000, v229
	v_fma_f32 v82, v82, v153, v152
	v_fma_f32 v83, v83, v155, v154
	v_cvt_pk_bf16_f32 v222, v84, v85
	v_cvt_pk_bf16_f32 v223, v86, v87
	v_cvt_pk_bf16_f32 v224, v80, v81
	v_cvt_pk_bf16_f32 v225, v82, v83
	s_add_u32 s28, s0, 0x10000
	s_addc_u32 s29, s1, 0
	global_store_dwordx4 v136, v[222:225], s[28:29] offset:256
	s_add_u32 s28, s0, 0x48000
	s_addc_u32 s29, s1, 0
	s_add_u32 s100, s26, 0x48000
	s_addc_u32 s101, s27, 0
	global_load_dwordx4 v[84:87], v136, s[28:29] offset:256
	global_load_dwordx4 v[80:83], v136, s[100:101] offset:256
	v_lshlrev_b32_e32 v148, 16, v222
	v_lshlrev_b32_e32 v149, 16, v223
	v_and_b32_e32 v150, 0xffff0000, v222
	v_and_b32_e32 v151, 0xffff0000, v223
	v_lshlrev_b32_e32 v152, 16, v224
	v_lshlrev_b32_e32 v153, 16, v225
	v_and_b32_e32 v154, 0xffff0000, v224
	v_and_b32_e32 v155, 0xffff0000, v225
	v_pk_mul_f32 v[150:151], v[150:151], v[150:151]
	v_pk_mul_f32 v[154:155], v[154:155], v[154:155]
	v_pk_fma_f32 v[148:149], v[148:149], v[148:149], v[150:151]
	v_pk_fma_f32 v[152:153], v[152:153], v[152:153], v[154:155]
	s_nop 0
	v_add_f32_e32 v148, v148, v149
	v_add_f32_e32 v152, v152, v153
	v_add_f32_e32 v158, v158, v148
	v_add_f32_e32 v158, v158, v152
	s_waitcnt vmcnt(15)
	v_permlane16_swap_b32_e32 v76, v72
	v_permlane16_swap_b32_e32 v77, v73
	v_permlane16_swap_b32_e32 v78, v74
	v_permlane16_swap_b32_e32 v79, v75
	v_mul_f32_e32 v76, 0xbfb8aa3b, v76
	v_mul_f32_e32 v77, 0xbfb8aa3b, v77
	v_mul_f32_e32 v78, 0xbfb8aa3b, v78
	v_mul_f32_e32 v79, 0xbfb8aa3b, v79
	v_mul_f32_e32 v72, 0xbfb8aa3b, v72
	v_mul_f32_e32 v73, 0xbfb8aa3b, v73
	v_mul_f32_e32 v74, 0xbfb8aa3b, v74
	v_mul_f32_e32 v75, 0xbfb8aa3b, v75
	v_exp_f32_e32 v76, v76
	v_exp_f32_e32 v77, v77
	v_exp_f32_e32 v78, v78
	v_exp_f32_e32 v79, v79
	v_exp_f32_e32 v72, v72
	v_exp_f32_e32 v73, v73
	v_exp_f32_e32 v74, v74
	v_exp_f32_e32 v75, v75
	v_add_f32_e32 v76, 1.0, v76
	v_add_f32_e32 v77, 1.0, v77
	v_add_f32_e32 v78, 1.0, v78
	v_add_f32_e32 v79, 1.0, v79
	v_add_f32_e32 v72, 1.0, v72
	v_add_f32_e32 v73, 1.0, v73
	v_add_f32_e32 v74, 1.0, v74
	v_add_f32_e32 v75, 1.0, v75
	v_rcp_f32_e32 v76, v76
	v_rcp_f32_e32 v77, v77
	v_rcp_f32_e32 v78, v78
	v_rcp_f32_e32 v79, v79
	v_rcp_f32_e32 v72, v72
	v_rcp_f32_e32 v73, v73
	v_rcp_f32_e32 v74, v74
	v_rcp_f32_e32 v75, v75
	v_lshlrev_b32_e32 v148, 16, v126
	v_lshlrev_b32_e32 v149, 16, v122
	v_and_b32_e32 v150, 0xffff0000, v126
	v_and_b32_e32 v151, 0xffff0000, v122
	v_fma_f32 v76, v76, v149, v148
	v_fma_f32 v77, v77, v151, v150
	v_lshlrev_b32_e32 v152, 16, v127
	v_lshlrev_b32_e32 v153, 16, v123
	v_and_b32_e32 v154, 0xffff0000, v127
	v_and_b32_e32 v155, 0xffff0000, v123
	v_fma_f32 v78, v78, v153, v152
	v_fma_f32 v79, v79, v155, v154
	v_lshlrev_b32_e32 v148, 16, v128
	v_lshlrev_b32_e32 v149, 16, v124
	v_and_b32_e32 v150, 0xffff0000, v128
	v_and_b32_e32 v151, 0xffff0000, v124
	v_fma_f32 v72, v72, v149, v148
	v_fma_f32 v73, v73, v151, v150
	v_lshlrev_b32_e32 v152, 16, v129
	v_lshlrev_b32_e32 v153, 16, v125
	v_and_b32_e32 v154, 0xffff0000, v129
	v_and_b32_e32 v155, 0xffff0000, v125
	v_fma_f32 v74, v74, v153, v152
	v_fma_f32 v75, v75, v155, v154
	v_cvt_pk_bf16_f32 v126, v76, v77
	v_cvt_pk_bf16_f32 v127, v78, v79
	v_cvt_pk_bf16_f32 v128, v72, v73
	v_cvt_pk_bf16_f32 v129, v74, v75
	s_add_u32 s28, s0, 0x18000
	s_addc_u32 s29, s1, 0
	global_store_dwordx4 v136, v[126:129], s[28:29]
	s_add_u32 s28, s0, 0x50000
	s_addc_u32 s29, s1, 0
	s_add_u32 s100, s26, 0x50000
	s_addc_u32 s101, s27, 0
	global_load_dwordx4 v[76:79], v136, s[28:29]
	global_load_dwordx4 v[72:75], v136, s[100:101]
	v_lshlrev_b32_e32 v148, 16, v126
	v_lshlrev_b32_e32 v149, 16, v127
	v_and_b32_e32 v150, 0xffff0000, v126
	v_and_b32_e32 v151, 0xffff0000, v127
	v_lshlrev_b32_e32 v152, 16, v128
	v_lshlrev_b32_e32 v153, 16, v129
	v_and_b32_e32 v154, 0xffff0000, v128
	v_and_b32_e32 v155, 0xffff0000, v129
	v_pk_mul_f32 v[150:151], v[150:151], v[150:151]
	v_pk_mul_f32 v[154:155], v[154:155], v[154:155]
	v_pk_fma_f32 v[148:149], v[148:149], v[148:149], v[150:151]
	v_pk_fma_f32 v[152:153], v[152:153], v[152:153], v[154:155]
	s_nop 0
	v_add_f32_e32 v148, v148, v149
	v_add_f32_e32 v152, v152, v153
	v_add_f32_e32 v159, v148, v152
	s_waitcnt vmcnt(15)
	v_permlane16_swap_b32_e32 v68, v64
	v_permlane16_swap_b32_e32 v69, v65
	v_permlane16_swap_b32_e32 v70, v66
	v_permlane16_swap_b32_e32 v71, v67
	v_mul_f32_e32 v68, 0xbfb8aa3b, v68
	v_mul_f32_e32 v69, 0xbfb8aa3b, v69
	v_mul_f32_e32 v70, 0xbfb8aa3b, v70
	v_mul_f32_e32 v71, 0xbfb8aa3b, v71
	v_mul_f32_e32 v64, 0xbfb8aa3b, v64
	v_mul_f32_e32 v65, 0xbfb8aa3b, v65
	v_mul_f32_e32 v66, 0xbfb8aa3b, v66
	v_mul_f32_e32 v67, 0xbfb8aa3b, v67
	v_exp_f32_e32 v68, v68
	v_exp_f32_e32 v69, v69
	v_exp_f32_e32 v70, v70
	v_exp_f32_e32 v71, v71
	v_exp_f32_e32 v64, v64
	v_exp_f32_e32 v65, v65
	v_exp_f32_e32 v66, v66
	v_exp_f32_e32 v67, v67
	v_add_f32_e32 v68, 1.0, v68
	v_add_f32_e32 v69, 1.0, v69
	v_add_f32_e32 v70, 1.0, v70
	v_add_f32_e32 v71, 1.0, v71
	v_add_f32_e32 v64, 1.0, v64
	v_add_f32_e32 v65, 1.0, v65
	v_add_f32_e32 v66, 1.0, v66
	v_add_f32_e32 v67, 1.0, v67
	v_rcp_f32_e32 v68, v68
	v_rcp_f32_e32 v69, v69
	v_rcp_f32_e32 v70, v70
	v_rcp_f32_e32 v71, v71
	v_rcp_f32_e32 v64, v64
	v_rcp_f32_e32 v65, v65
	v_rcp_f32_e32 v66, v66
	v_rcp_f32_e32 v67, v67
	v_lshlrev_b32_e32 v148, 16, v118
	v_lshlrev_b32_e32 v149, 16, v114
	v_and_b32_e32 v150, 0xffff0000, v118
	v_and_b32_e32 v151, 0xffff0000, v114
	v_fma_f32 v68, v68, v149, v148
	v_fma_f32 v69, v69, v151, v150
	v_lshlrev_b32_e32 v152, 16, v119
	v_lshlrev_b32_e32 v153, 16, v115
	v_and_b32_e32 v154, 0xffff0000, v119
	v_and_b32_e32 v155, 0xffff0000, v115
	v_fma_f32 v70, v70, v153, v152
	v_fma_f32 v71, v71, v155, v154
	v_lshlrev_b32_e32 v148, 16, v120
	v_lshlrev_b32_e32 v149, 16, v116
	v_and_b32_e32 v150, 0xffff0000, v120
	v_and_b32_e32 v151, 0xffff0000, v116
	v_fma_f32 v64, v64, v149, v148
	v_fma_f32 v65, v65, v151, v150
	v_lshlrev_b32_e32 v152, 16, v121
	v_lshlrev_b32_e32 v153, 16, v117
	v_and_b32_e32 v154, 0xffff0000, v121
	v_and_b32_e32 v155, 0xffff0000, v117
	v_fma_f32 v66, v66, v153, v152
	v_fma_f32 v67, v67, v155, v154
	v_cvt_pk_bf16_f32 v118, v68, v69
	v_cvt_pk_bf16_f32 v119, v70, v71
	v_cvt_pk_bf16_f32 v120, v64, v65
	v_cvt_pk_bf16_f32 v121, v66, v67
	s_add_u32 s28, s0, 0x18000
	s_addc_u32 s29, s1, 0
	global_store_dwordx4 v136, v[118:121], s[28:29] offset:256
	s_add_u32 s28, s0, 0x50000
	s_addc_u32 s29, s1, 0
	s_add_u32 s100, s26, 0x50000
	s_addc_u32 s101, s27, 0
	global_load_dwordx4 v[68:71], v136, s[28:29] offset:256
	global_load_dwordx4 v[64:67], v136, s[100:101] offset:256
	v_lshlrev_b32_e32 v148, 16, v118
	v_lshlrev_b32_e32 v149, 16, v119
	v_and_b32_e32 v150, 0xffff0000, v118
	v_and_b32_e32 v151, 0xffff0000, v119
	v_lshlrev_b32_e32 v152, 16, v120
	v_lshlrev_b32_e32 v153, 16, v121
	v_and_b32_e32 v154, 0xffff0000, v120
	v_and_b32_e32 v155, 0xffff0000, v121
	v_pk_mul_f32 v[150:151], v[150:151], v[150:151]
	v_pk_mul_f32 v[154:155], v[154:155], v[154:155]
	v_pk_fma_f32 v[148:149], v[148:149], v[148:149], v[150:151]
	v_pk_fma_f32 v[152:153], v[152:153], v[152:153], v[154:155]
	s_nop 0
	v_add_f32_e32 v148, v148, v149
	v_add_f32_e32 v152, v152, v153
	v_add_f32_e32 v159, v159, v148
	v_add_f32_e32 v159, v159, v152
	ds_bpermute_b32 v148, v137, v156
	ds_bpermute_b32 v149, v137, v157
	ds_bpermute_b32 v150, v137, v158
	ds_bpermute_b32 v151, v137, v159
	s_waitcnt lgkmcnt(0)
	v_add_f32_e32 v156, v156, v148
	v_add_f32_e32 v157, v157, v149
	v_add_f32_e32 v158, v158, v150
	v_add_f32_e32 v159, v159, v151
	ds_bpermute_b32 v148, v138, v156
	ds_bpermute_b32 v149, v138, v157
	ds_bpermute_b32 v150, v138, v158
	ds_bpermute_b32 v151, v138, v159
	s_waitcnt lgkmcnt(0)
	v_add_f32_e32 v156, v156, v148
	v_add_f32_e32 v157, v157, v149
	v_add_f32_e32 v158, v158, v150
	v_add_f32_e32 v159, v159, v151
	s_and_saveexec_b64 vcc, s[4:5]
	ds_write_b32 v146, v156
	ds_write_b32 v146, v157 offset:256
	ds_write_b32 v146, v158 offset:512
	ds_write_b32 v146, v159 offset:768
	s_or_b64 exec, exec, vcc
	s_waitcnt vmcnt(15)
	v_permlane16_swap_b32_e32 v60, v56
	v_permlane16_swap_b32_e32 v61, v57
	v_permlane16_swap_b32_e32 v62, v58
	v_permlane16_swap_b32_e32 v63, v59
	v_mul_f32_e32 v60, 0xbfb8aa3b, v60
	v_mul_f32_e32 v61, 0xbfb8aa3b, v61
	v_mul_f32_e32 v62, 0xbfb8aa3b, v62
	v_mul_f32_e32 v63, 0xbfb8aa3b, v63
	v_mul_f32_e32 v56, 0xbfb8aa3b, v56
	v_mul_f32_e32 v57, 0xbfb8aa3b, v57
	v_mul_f32_e32 v58, 0xbfb8aa3b, v58
	v_mul_f32_e32 v59, 0xbfb8aa3b, v59
	v_exp_f32_e32 v60, v60
	v_exp_f32_e32 v61, v61
	v_exp_f32_e32 v62, v62
	v_exp_f32_e32 v63, v63
	v_exp_f32_e32 v56, v56
	v_exp_f32_e32 v57, v57
	v_exp_f32_e32 v58, v58
	v_exp_f32_e32 v59, v59
	v_add_f32_e32 v60, 1.0, v60
	v_add_f32_e32 v61, 1.0, v61
	v_add_f32_e32 v62, 1.0, v62
	v_add_f32_e32 v63, 1.0, v63
	v_add_f32_e32 v56, 1.0, v56
	v_add_f32_e32 v57, 1.0, v57
	v_add_f32_e32 v58, 1.0, v58
	v_add_f32_e32 v59, 1.0, v59
	v_rcp_f32_e32 v60, v60
	v_rcp_f32_e32 v61, v61
	v_rcp_f32_e32 v62, v62
	v_rcp_f32_e32 v63, v63
	v_rcp_f32_e32 v56, v56
	v_rcp_f32_e32 v57, v57
	v_rcp_f32_e32 v58, v58
	v_rcp_f32_e32 v59, v59
	v_lshlrev_b32_e32 v148, 16, v110
	v_lshlrev_b32_e32 v149, 16, v106
	v_and_b32_e32 v150, 0xffff0000, v110
	v_and_b32_e32 v151, 0xffff0000, v106
	v_fma_f32 v60, v60, v149, v148
	v_fma_f32 v61, v61, v151, v150
	v_lshlrev_b32_e32 v152, 16, v111
	v_lshlrev_b32_e32 v153, 16, v107
	v_and_b32_e32 v154, 0xffff0000, v111
	v_and_b32_e32 v155, 0xffff0000, v107
	v_fma_f32 v62, v62, v153, v152
	v_fma_f32 v63, v63, v155, v154
	v_lshlrev_b32_e32 v148, 16, v112
	v_lshlrev_b32_e32 v149, 16, v108
	v_and_b32_e32 v150, 0xffff0000, v112
	v_and_b32_e32 v151, 0xffff0000, v108
	v_fma_f32 v56, v56, v149, v148
	v_fma_f32 v57, v57, v151, v150
	v_lshlrev_b32_e32 v152, 16, v113
	v_lshlrev_b32_e32 v153, 16, v109
	v_and_b32_e32 v154, 0xffff0000, v113
	v_and_b32_e32 v155, 0xffff0000, v109
	v_fma_f32 v58, v58, v153, v152
	v_fma_f32 v59, v59, v155, v154
	v_cvt_pk_bf16_f32 v110, v60, v61
	v_cvt_pk_bf16_f32 v111, v62, v63
	v_cvt_pk_bf16_f32 v112, v56, v57
	v_cvt_pk_bf16_f32 v113, v58, v59
	s_add_u32 s28, s0, 0x40000
	s_addc_u32 s29, s1, 0
	global_store_dwordx4 v136, v[110:113], s[28:29]
	s_add_u32 s28, s0, 0x58000
	s_addc_u32 s29, s1, 0
	s_add_u32 s100, s26, 0x58000
	s_addc_u32 s101, s27, 0
	global_load_dwordx4 v[60:63], v136, s[28:29]
	global_load_dwordx4 v[56:59], v136, s[100:101]
	v_lshlrev_b32_e32 v148, 16, v110
	v_lshlrev_b32_e32 v149, 16, v111
	v_and_b32_e32 v150, 0xffff0000, v110
	v_and_b32_e32 v151, 0xffff0000, v111
	v_lshlrev_b32_e32 v152, 16, v112
	v_lshlrev_b32_e32 v153, 16, v113
	v_and_b32_e32 v154, 0xffff0000, v112
	v_and_b32_e32 v155, 0xffff0000, v113
	v_pk_mul_f32 v[150:151], v[150:151], v[150:151]
	v_pk_mul_f32 v[154:155], v[154:155], v[154:155]
	v_pk_fma_f32 v[148:149], v[148:149], v[148:149], v[150:151]
	v_pk_fma_f32 v[152:153], v[152:153], v[152:153], v[154:155]
	s_nop 0
	v_add_f32_e32 v148, v148, v149
	v_add_f32_e32 v152, v152, v153
	v_add_f32_e32 v156, v148, v152
	s_waitcnt vmcnt(15)
	v_permlane16_swap_b32_e32 v52, v48
	v_permlane16_swap_b32_e32 v53, v49
	v_permlane16_swap_b32_e32 v54, v50
	v_permlane16_swap_b32_e32 v55, v51
	v_mul_f32_e32 v52, 0xbfb8aa3b, v52
	v_mul_f32_e32 v53, 0xbfb8aa3b, v53
	v_mul_f32_e32 v54, 0xbfb8aa3b, v54
	v_mul_f32_e32 v55, 0xbfb8aa3b, v55
	v_mul_f32_e32 v48, 0xbfb8aa3b, v48
	v_mul_f32_e32 v49, 0xbfb8aa3b, v49
	v_mul_f32_e32 v50, 0xbfb8aa3b, v50
	v_mul_f32_e32 v51, 0xbfb8aa3b, v51
	v_exp_f32_e32 v52, v52
	v_exp_f32_e32 v53, v53
	v_exp_f32_e32 v54, v54
	v_exp_f32_e32 v55, v55
	v_exp_f32_e32 v48, v48
	v_exp_f32_e32 v49, v49
	v_exp_f32_e32 v50, v50
	v_exp_f32_e32 v51, v51
	v_add_f32_e32 v52, 1.0, v52
	v_add_f32_e32 v53, 1.0, v53
	v_add_f32_e32 v54, 1.0, v54
	v_add_f32_e32 v55, 1.0, v55
	v_add_f32_e32 v48, 1.0, v48
	v_add_f32_e32 v49, 1.0, v49
	v_add_f32_e32 v50, 1.0, v50
	v_add_f32_e32 v51, 1.0, v51
	v_rcp_f32_e32 v52, v52
	v_rcp_f32_e32 v53, v53
	v_rcp_f32_e32 v54, v54
	v_rcp_f32_e32 v55, v55
	v_rcp_f32_e32 v48, v48
	v_rcp_f32_e32 v49, v49
	v_rcp_f32_e32 v50, v50
	v_rcp_f32_e32 v51, v51
	v_lshlrev_b32_e32 v148, 16, v102
	v_lshlrev_b32_e32 v149, 16, v98
	v_and_b32_e32 v150, 0xffff0000, v102
	v_and_b32_e32 v151, 0xffff0000, v98
	v_fma_f32 v52, v52, v149, v148
	v_fma_f32 v53, v53, v151, v150
	v_lshlrev_b32_e32 v152, 16, v103
	v_lshlrev_b32_e32 v153, 16, v99
	v_and_b32_e32 v154, 0xffff0000, v103
	v_and_b32_e32 v155, 0xffff0000, v99
	v_fma_f32 v54, v54, v153, v152
	v_fma_f32 v55, v55, v155, v154
	v_lshlrev_b32_e32 v148, 16, v104
	v_lshlrev_b32_e32 v149, 16, v100
	v_and_b32_e32 v150, 0xffff0000, v104
	v_and_b32_e32 v151, 0xffff0000, v100
	v_fma_f32 v48, v48, v149, v148
	v_fma_f32 v49, v49, v151, v150
	v_lshlrev_b32_e32 v152, 16, v105
	v_lshlrev_b32_e32 v153, 16, v101
	v_and_b32_e32 v154, 0xffff0000, v105
	v_and_b32_e32 v155, 0xffff0000, v101
	v_fma_f32 v50, v50, v153, v152
	v_fma_f32 v51, v51, v155, v154
	v_cvt_pk_bf16_f32 v102, v52, v53
	v_cvt_pk_bf16_f32 v103, v54, v55
	v_cvt_pk_bf16_f32 v104, v48, v49
	v_cvt_pk_bf16_f32 v105, v50, v51
	s_add_u32 s28, s0, 0x40000
	s_addc_u32 s29, s1, 0
	global_store_dwordx4 v136, v[102:105], s[28:29] offset:256
	s_add_u32 s28, s0, 0x58000
	s_addc_u32 s29, s1, 0
	s_add_u32 s100, s26, 0x58000
	s_addc_u32 s101, s27, 0
	global_load_dwordx4 v[52:55], v136, s[28:29] offset:256
	global_load_dwordx4 v[48:51], v136, s[100:101] offset:256
	v_lshlrev_b32_e32 v148, 16, v102
	v_lshlrev_b32_e32 v149, 16, v103
	v_and_b32_e32 v150, 0xffff0000, v102
	v_and_b32_e32 v151, 0xffff0000, v103
	v_lshlrev_b32_e32 v152, 16, v104
	v_lshlrev_b32_e32 v153, 16, v105
	v_and_b32_e32 v154, 0xffff0000, v104
	v_and_b32_e32 v155, 0xffff0000, v105
	v_pk_mul_f32 v[150:151], v[150:151], v[150:151]
	v_pk_mul_f32 v[154:155], v[154:155], v[154:155]
	v_pk_fma_f32 v[148:149], v[148:149], v[148:149], v[150:151]
	v_pk_fma_f32 v[152:153], v[152:153], v[152:153], v[154:155]
	s_nop 0
	v_add_f32_e32 v148, v148, v149
	v_add_f32_e32 v152, v152, v153
	v_add_f32_e32 v156, v156, v148
	v_add_f32_e32 v156, v156, v152
	s_waitcnt vmcnt(15)
	v_permlane16_swap_b32_e32 v44, v40
	v_permlane16_swap_b32_e32 v45, v41
	v_permlane16_swap_b32_e32 v46, v42
	v_permlane16_swap_b32_e32 v47, v43
	v_mul_f32_e32 v44, 0xbfb8aa3b, v44
	v_mul_f32_e32 v45, 0xbfb8aa3b, v45
	v_mul_f32_e32 v46, 0xbfb8aa3b, v46
	v_mul_f32_e32 v47, 0xbfb8aa3b, v47
	v_mul_f32_e32 v40, 0xbfb8aa3b, v40
	v_mul_f32_e32 v41, 0xbfb8aa3b, v41
	v_mul_f32_e32 v42, 0xbfb8aa3b, v42
	v_mul_f32_e32 v43, 0xbfb8aa3b, v43
	v_exp_f32_e32 v44, v44
	v_exp_f32_e32 v45, v45
	v_exp_f32_e32 v46, v46
	v_exp_f32_e32 v47, v47
	v_exp_f32_e32 v40, v40
	v_exp_f32_e32 v41, v41
	v_exp_f32_e32 v42, v42
	v_exp_f32_e32 v43, v43
	v_add_f32_e32 v44, 1.0, v44
	v_add_f32_e32 v45, 1.0, v45
	v_add_f32_e32 v46, 1.0, v46
	v_add_f32_e32 v47, 1.0, v47
	v_add_f32_e32 v40, 1.0, v40
	v_add_f32_e32 v41, 1.0, v41
	v_add_f32_e32 v42, 1.0, v42
	v_add_f32_e32 v43, 1.0, v43
	v_rcp_f32_e32 v44, v44
	v_rcp_f32_e32 v45, v45
	v_rcp_f32_e32 v46, v46
	v_rcp_f32_e32 v47, v47
	v_rcp_f32_e32 v40, v40
	v_rcp_f32_e32 v41, v41
	v_rcp_f32_e32 v42, v42
	v_rcp_f32_e32 v43, v43
	v_lshlrev_b32_e32 v148, 16, v92
	v_lshlrev_b32_e32 v149, 16, v88
	v_and_b32_e32 v150, 0xffff0000, v92
	v_and_b32_e32 v151, 0xffff0000, v88
	v_fma_f32 v44, v44, v149, v148
	v_fma_f32 v45, v45, v151, v150
	v_lshlrev_b32_e32 v152, 16, v93
	v_lshlrev_b32_e32 v153, 16, v89
	v_and_b32_e32 v154, 0xffff0000, v93
	v_and_b32_e32 v155, 0xffff0000, v89
	v_fma_f32 v46, v46, v153, v152
	v_fma_f32 v47, v47, v155, v154
	v_lshlrev_b32_e32 v148, 16, v94
	v_lshlrev_b32_e32 v149, 16, v90
	v_and_b32_e32 v150, 0xffff0000, v94
	v_and_b32_e32 v151, 0xffff0000, v90
	v_fma_f32 v40, v40, v149, v148
	v_fma_f32 v41, v41, v151, v150
	v_lshlrev_b32_e32 v152, 16, v95
	v_lshlrev_b32_e32 v153, 16, v91
	v_and_b32_e32 v154, 0xffff0000, v95
	v_and_b32_e32 v155, 0xffff0000, v91
	v_fma_f32 v42, v42, v153, v152
	v_fma_f32 v43, v43, v155, v154
	v_cvt_pk_bf16_f32 v92, v44, v45
	v_cvt_pk_bf16_f32 v93, v46, v47
	v_cvt_pk_bf16_f32 v94, v40, v41
	v_cvt_pk_bf16_f32 v95, v42, v43
	s_add_u32 s28, s0, 0x48000
	s_addc_u32 s29, s1, 0
	global_store_dwordx4 v136, v[92:95], s[28:29]
	v_lshlrev_b32_e32 v148, 16, v92
	v_lshlrev_b32_e32 v149, 16, v93
	v_and_b32_e32 v150, 0xffff0000, v92
	v_and_b32_e32 v151, 0xffff0000, v93
	v_lshlrev_b32_e32 v152, 16, v94
	v_lshlrev_b32_e32 v153, 16, v95
	v_and_b32_e32 v154, 0xffff0000, v94
	v_and_b32_e32 v155, 0xffff0000, v95
	v_pk_mul_f32 v[150:151], v[150:151], v[150:151]
	v_pk_mul_f32 v[154:155], v[154:155], v[154:155]
	v_pk_fma_f32 v[148:149], v[148:149], v[148:149], v[150:151]
	v_pk_fma_f32 v[152:153], v[152:153], v[152:153], v[154:155]
	s_nop 0
	v_add_f32_e32 v148, v148, v149
	v_add_f32_e32 v152, v152, v153
	v_add_f32_e32 v157, v148, v152
	s_waitcnt vmcnt(13)
	v_permlane16_swap_b32_e32 v36, v32
	v_permlane16_swap_b32_e32 v37, v33
	v_permlane16_swap_b32_e32 v38, v34
	v_permlane16_swap_b32_e32 v39, v35
	v_mul_f32_e32 v36, 0xbfb8aa3b, v36
	v_mul_f32_e32 v37, 0xbfb8aa3b, v37
	v_mul_f32_e32 v38, 0xbfb8aa3b, v38
	v_mul_f32_e32 v39, 0xbfb8aa3b, v39
	v_mul_f32_e32 v32, 0xbfb8aa3b, v32
	v_mul_f32_e32 v33, 0xbfb8aa3b, v33
	v_mul_f32_e32 v34, 0xbfb8aa3b, v34
	v_mul_f32_e32 v35, 0xbfb8aa3b, v35
	v_exp_f32_e32 v36, v36
	v_exp_f32_e32 v37, v37
	v_exp_f32_e32 v38, v38
	v_exp_f32_e32 v39, v39
	v_exp_f32_e32 v32, v32
	v_exp_f32_e32 v33, v33
	v_exp_f32_e32 v34, v34
	v_exp_f32_e32 v35, v35
	v_add_f32_e32 v36, 1.0, v36
	v_add_f32_e32 v37, 1.0, v37
	v_add_f32_e32 v38, 1.0, v38
	v_add_f32_e32 v39, 1.0, v39
	v_add_f32_e32 v32, 1.0, v32
	v_add_f32_e32 v33, 1.0, v33
	v_add_f32_e32 v34, 1.0, v34
	v_add_f32_e32 v35, 1.0, v35
	v_rcp_f32_e32 v36, v36
	v_rcp_f32_e32 v37, v37
	v_rcp_f32_e32 v38, v38
	v_rcp_f32_e32 v39, v39
	v_rcp_f32_e32 v32, v32
	v_rcp_f32_e32 v33, v33
	v_rcp_f32_e32 v34, v34
	v_rcp_f32_e32 v35, v35
	v_lshlrev_b32_e32 v148, 16, v84
	v_lshlrev_b32_e32 v149, 16, v80
	v_and_b32_e32 v150, 0xffff0000, v84
	v_and_b32_e32 v151, 0xffff0000, v80
	v_fma_f32 v36, v36, v149, v148
	v_fma_f32 v37, v37, v151, v150
	v_lshlrev_b32_e32 v152, 16, v85
	v_lshlrev_b32_e32 v153, 16, v81
	v_and_b32_e32 v154, 0xffff0000, v85
	v_and_b32_e32 v155, 0xffff0000, v81
	v_fma_f32 v38, v38, v153, v152
	v_fma_f32 v39, v39, v155, v154
	v_lshlrev_b32_e32 v148, 16, v86
	v_lshlrev_b32_e32 v149, 16, v82
	v_and_b32_e32 v150, 0xffff0000, v86
	v_and_b32_e32 v151, 0xffff0000, v82
	v_fma_f32 v32, v32, v149, v148
	v_fma_f32 v33, v33, v151, v150
	v_lshlrev_b32_e32 v152, 16, v87
	v_lshlrev_b32_e32 v153, 16, v83
	v_and_b32_e32 v154, 0xffff0000, v87
	v_and_b32_e32 v155, 0xffff0000, v83
	v_fma_f32 v34, v34, v153, v152
	v_fma_f32 v35, v35, v155, v154
	v_cvt_pk_bf16_f32 v84, v36, v37
	v_cvt_pk_bf16_f32 v85, v38, v39
	v_cvt_pk_bf16_f32 v86, v32, v33
	v_cvt_pk_bf16_f32 v87, v34, v35
	s_add_u32 s28, s0, 0x48000
	s_addc_u32 s29, s1, 0
	global_store_dwordx4 v136, v[84:87], s[28:29] offset:256
	v_lshlrev_b32_e32 v148, 16, v84
	v_lshlrev_b32_e32 v149, 16, v85
	v_and_b32_e32 v150, 0xffff0000, v84
	v_and_b32_e32 v151, 0xffff0000, v85
	v_lshlrev_b32_e32 v152, 16, v86
	v_lshlrev_b32_e32 v153, 16, v87
	v_and_b32_e32 v154, 0xffff0000, v86
	v_and_b32_e32 v155, 0xffff0000, v87
	v_pk_mul_f32 v[150:151], v[150:151], v[150:151]
	v_pk_mul_f32 v[154:155], v[154:155], v[154:155]
	v_pk_fma_f32 v[148:149], v[148:149], v[148:149], v[150:151]
	v_pk_fma_f32 v[152:153], v[152:153], v[152:153], v[154:155]
	s_nop 0
	v_add_f32_e32 v148, v148, v149
	v_add_f32_e32 v152, v152, v153
	v_add_f32_e32 v157, v157, v148
	v_add_f32_e32 v157, v157, v152
	s_waitcnt vmcnt(11)
	v_permlane16_swap_b32_e32 v28, v24
	v_permlane16_swap_b32_e32 v29, v25
	v_permlane16_swap_b32_e32 v30, v26
	v_permlane16_swap_b32_e32 v31, v27
	v_mul_f32_e32 v28, 0xbfb8aa3b, v28
	v_mul_f32_e32 v29, 0xbfb8aa3b, v29
	v_mul_f32_e32 v30, 0xbfb8aa3b, v30
	v_mul_f32_e32 v31, 0xbfb8aa3b, v31
	v_mul_f32_e32 v24, 0xbfb8aa3b, v24
	v_mul_f32_e32 v25, 0xbfb8aa3b, v25
	v_mul_f32_e32 v26, 0xbfb8aa3b, v26
	v_mul_f32_e32 v27, 0xbfb8aa3b, v27
	v_exp_f32_e32 v28, v28
	v_exp_f32_e32 v29, v29
	v_exp_f32_e32 v30, v30
	v_exp_f32_e32 v31, v31
	v_exp_f32_e32 v24, v24
	v_exp_f32_e32 v25, v25
	v_exp_f32_e32 v26, v26
	v_exp_f32_e32 v27, v27
	v_add_f32_e32 v28, 1.0, v28
	v_add_f32_e32 v29, 1.0, v29
	v_add_f32_e32 v30, 1.0, v30
	v_add_f32_e32 v31, 1.0, v31
	v_add_f32_e32 v24, 1.0, v24
	v_add_f32_e32 v25, 1.0, v25
	v_add_f32_e32 v26, 1.0, v26
	v_add_f32_e32 v27, 1.0, v27
	v_rcp_f32_e32 v28, v28
	v_rcp_f32_e32 v29, v29
	v_rcp_f32_e32 v30, v30
	v_rcp_f32_e32 v31, v31
	v_rcp_f32_e32 v24, v24
	v_rcp_f32_e32 v25, v25
	v_rcp_f32_e32 v26, v26
	v_rcp_f32_e32 v27, v27
	v_lshlrev_b32_e32 v148, 16, v76
	v_lshlrev_b32_e32 v149, 16, v72
	v_and_b32_e32 v150, 0xffff0000, v76
	v_and_b32_e32 v151, 0xffff0000, v72
	v_fma_f32 v28, v28, v149, v148
	v_fma_f32 v29, v29, v151, v150
	v_lshlrev_b32_e32 v152, 16, v77
	v_lshlrev_b32_e32 v153, 16, v73
	v_and_b32_e32 v154, 0xffff0000, v77
	v_and_b32_e32 v155, 0xffff0000, v73
	v_fma_f32 v30, v30, v153, v152
	v_fma_f32 v31, v31, v155, v154
	v_lshlrev_b32_e32 v148, 16, v78
	v_lshlrev_b32_e32 v149, 16, v74
	v_and_b32_e32 v150, 0xffff0000, v78
	v_and_b32_e32 v151, 0xffff0000, v74
	v_fma_f32 v24, v24, v149, v148
	v_fma_f32 v25, v25, v151, v150
	v_lshlrev_b32_e32 v152, 16, v79
	v_lshlrev_b32_e32 v153, 16, v75
	v_and_b32_e32 v154, 0xffff0000, v79
	v_and_b32_e32 v155, 0xffff0000, v75
	v_fma_f32 v26, v26, v153, v152
	v_fma_f32 v27, v27, v155, v154
	v_cvt_pk_bf16_f32 v76, v28, v29
	v_cvt_pk_bf16_f32 v77, v30, v31
	v_cvt_pk_bf16_f32 v78, v24, v25
	v_cvt_pk_bf16_f32 v79, v26, v27
	s_add_u32 s28, s0, 0x50000
	s_addc_u32 s29, s1, 0
	global_store_dwordx4 v136, v[76:79], s[28:29]
	v_lshlrev_b32_e32 v148, 16, v76
	v_lshlrev_b32_e32 v149, 16, v77
	v_and_b32_e32 v150, 0xffff0000, v76
	v_and_b32_e32 v151, 0xffff0000, v77
	v_lshlrev_b32_e32 v152, 16, v78
	v_lshlrev_b32_e32 v153, 16, v79
	v_and_b32_e32 v154, 0xffff0000, v78
	v_and_b32_e32 v155, 0xffff0000, v79
	v_pk_mul_f32 v[150:151], v[150:151], v[150:151]
	v_pk_mul_f32 v[154:155], v[154:155], v[154:155]
	v_pk_fma_f32 v[148:149], v[148:149], v[148:149], v[150:151]
	v_pk_fma_f32 v[152:153], v[152:153], v[152:153], v[154:155]
	s_nop 0
	v_add_f32_e32 v148, v148, v149
	v_add_f32_e32 v152, v152, v153
	v_add_f32_e32 v158, v148, v152
	s_waitcnt vmcnt(9)
	v_permlane16_swap_b32_e32 v20, v16
	v_permlane16_swap_b32_e32 v21, v17
	v_permlane16_swap_b32_e32 v22, v18
	v_permlane16_swap_b32_e32 v23, v19
	v_mul_f32_e32 v20, 0xbfb8aa3b, v20
	v_mul_f32_e32 v21, 0xbfb8aa3b, v21
	v_mul_f32_e32 v22, 0xbfb8aa3b, v22
	v_mul_f32_e32 v23, 0xbfb8aa3b, v23
	v_mul_f32_e32 v16, 0xbfb8aa3b, v16
	v_mul_f32_e32 v17, 0xbfb8aa3b, v17
	v_mul_f32_e32 v18, 0xbfb8aa3b, v18
	v_mul_f32_e32 v19, 0xbfb8aa3b, v19
	v_exp_f32_e32 v20, v20
	v_exp_f32_e32 v21, v21
	v_exp_f32_e32 v22, v22
	v_exp_f32_e32 v23, v23
	v_exp_f32_e32 v16, v16
	v_exp_f32_e32 v17, v17
	v_exp_f32_e32 v18, v18
	v_exp_f32_e32 v19, v19
	v_add_f32_e32 v20, 1.0, v20
	v_add_f32_e32 v21, 1.0, v21
	v_add_f32_e32 v22, 1.0, v22
	v_add_f32_e32 v23, 1.0, v23
	v_add_f32_e32 v16, 1.0, v16
	v_add_f32_e32 v17, 1.0, v17
	v_add_f32_e32 v18, 1.0, v18
	v_add_f32_e32 v19, 1.0, v19
	v_rcp_f32_e32 v20, v20
	v_rcp_f32_e32 v21, v21
	v_rcp_f32_e32 v22, v22
	v_rcp_f32_e32 v23, v23
	v_rcp_f32_e32 v16, v16
	v_rcp_f32_e32 v17, v17
	v_rcp_f32_e32 v18, v18
	v_rcp_f32_e32 v19, v19
	v_lshlrev_b32_e32 v148, 16, v68
	v_lshlrev_b32_e32 v149, 16, v64
	v_and_b32_e32 v150, 0xffff0000, v68
	v_and_b32_e32 v151, 0xffff0000, v64
	v_fma_f32 v20, v20, v149, v148
	v_fma_f32 v21, v21, v151, v150
	v_lshlrev_b32_e32 v152, 16, v69
	v_lshlrev_b32_e32 v153, 16, v65
	v_and_b32_e32 v154, 0xffff0000, v69
	v_and_b32_e32 v155, 0xffff0000, v65
	v_fma_f32 v22, v22, v153, v152
	v_fma_f32 v23, v23, v155, v154
	v_lshlrev_b32_e32 v148, 16, v70
	v_lshlrev_b32_e32 v149, 16, v66
	v_and_b32_e32 v150, 0xffff0000, v70
	v_and_b32_e32 v151, 0xffff0000, v66
	v_fma_f32 v16, v16, v149, v148
	v_fma_f32 v17, v17, v151, v150
	v_lshlrev_b32_e32 v152, 16, v71
	v_lshlrev_b32_e32 v153, 16, v67
	v_and_b32_e32 v154, 0xffff0000, v71
	v_and_b32_e32 v155, 0xffff0000, v67
	v_fma_f32 v18, v18, v153, v152
	v_fma_f32 v19, v19, v155, v154
	v_cvt_pk_bf16_f32 v68, v20, v21
	v_cvt_pk_bf16_f32 v69, v22, v23
	v_cvt_pk_bf16_f32 v70, v16, v17
	v_cvt_pk_bf16_f32 v71, v18, v19
	s_add_u32 s28, s0, 0x50000
	s_addc_u32 s29, s1, 0
	global_store_dwordx4 v136, v[68:71], s[28:29] offset:256
	v_lshlrev_b32_e32 v148, 16, v68
	v_lshlrev_b32_e32 v149, 16, v69
	v_and_b32_e32 v150, 0xffff0000, v68
	v_and_b32_e32 v151, 0xffff0000, v69
	v_lshlrev_b32_e32 v152, 16, v70
	v_lshlrev_b32_e32 v153, 16, v71
	v_and_b32_e32 v154, 0xffff0000, v70
	v_and_b32_e32 v155, 0xffff0000, v71
	v_pk_mul_f32 v[150:151], v[150:151], v[150:151]
	v_pk_mul_f32 v[154:155], v[154:155], v[154:155]
	v_pk_fma_f32 v[148:149], v[148:149], v[148:149], v[150:151]
	v_pk_fma_f32 v[152:153], v[152:153], v[152:153], v[154:155]
	s_nop 0
	v_add_f32_e32 v148, v148, v149
	v_add_f32_e32 v152, v152, v153
	v_add_f32_e32 v158, v158, v148
	v_add_f32_e32 v158, v158, v152
	s_waitcnt vmcnt(7)
	v_permlane16_swap_b32_e32 v12, v8
	v_permlane16_swap_b32_e32 v13, v9
	v_permlane16_swap_b32_e32 v14, v10
	v_permlane16_swap_b32_e32 v15, v11
	v_mul_f32_e32 v12, 0xbfb8aa3b, v12
	v_mul_f32_e32 v13, 0xbfb8aa3b, v13
	v_mul_f32_e32 v14, 0xbfb8aa3b, v14
	v_mul_f32_e32 v15, 0xbfb8aa3b, v15
	v_mul_f32_e32 v8, 0xbfb8aa3b, v8
	v_mul_f32_e32 v9, 0xbfb8aa3b, v9
	v_mul_f32_e32 v10, 0xbfb8aa3b, v10
	v_mul_f32_e32 v11, 0xbfb8aa3b, v11
	v_exp_f32_e32 v12, v12
	v_exp_f32_e32 v13, v13
	v_exp_f32_e32 v14, v14
	v_exp_f32_e32 v15, v15
	v_exp_f32_e32 v8, v8
	v_exp_f32_e32 v9, v9
	v_exp_f32_e32 v10, v10
	v_exp_f32_e32 v11, v11
	v_add_f32_e32 v12, 1.0, v12
	v_add_f32_e32 v13, 1.0, v13
	v_add_f32_e32 v14, 1.0, v14
	v_add_f32_e32 v15, 1.0, v15
	v_add_f32_e32 v8, 1.0, v8
	v_add_f32_e32 v9, 1.0, v9
	v_add_f32_e32 v10, 1.0, v10
	v_add_f32_e32 v11, 1.0, v11
	v_rcp_f32_e32 v12, v12
	v_rcp_f32_e32 v13, v13
	v_rcp_f32_e32 v14, v14
	v_rcp_f32_e32 v15, v15
	v_rcp_f32_e32 v8, v8
	v_rcp_f32_e32 v9, v9
	v_rcp_f32_e32 v10, v10
	v_rcp_f32_e32 v11, v11
	v_lshlrev_b32_e32 v148, 16, v60
	v_lshlrev_b32_e32 v149, 16, v56
	v_and_b32_e32 v150, 0xffff0000, v60
	v_and_b32_e32 v151, 0xffff0000, v56
	v_fma_f32 v12, v12, v149, v148
	v_fma_f32 v13, v13, v151, v150
	v_lshlrev_b32_e32 v152, 16, v61
	v_lshlrev_b32_e32 v153, 16, v57
	v_and_b32_e32 v154, 0xffff0000, v61
	v_and_b32_e32 v155, 0xffff0000, v57
	v_fma_f32 v14, v14, v153, v152
	v_fma_f32 v15, v15, v155, v154
	v_lshlrev_b32_e32 v148, 16, v62
	v_lshlrev_b32_e32 v149, 16, v58
	v_and_b32_e32 v150, 0xffff0000, v62
	v_and_b32_e32 v151, 0xffff0000, v58
	v_fma_f32 v8, v8, v149, v148
	v_fma_f32 v9, v9, v151, v150
	v_lshlrev_b32_e32 v152, 16, v63
	v_lshlrev_b32_e32 v153, 16, v59
	v_and_b32_e32 v154, 0xffff0000, v63
	v_and_b32_e32 v155, 0xffff0000, v59
	v_fma_f32 v10, v10, v153, v152
	v_fma_f32 v11, v11, v155, v154
	v_cvt_pk_bf16_f32 v60, v12, v13
	v_cvt_pk_bf16_f32 v61, v14, v15
	v_cvt_pk_bf16_f32 v62, v8, v9
	v_cvt_pk_bf16_f32 v63, v10, v11
	s_add_u32 s28, s0, 0x58000
	s_addc_u32 s29, s1, 0
	global_store_dwordx4 v136, v[60:63], s[28:29]
	v_lshlrev_b32_e32 v148, 16, v60
	v_lshlrev_b32_e32 v149, 16, v61
	v_and_b32_e32 v150, 0xffff0000, v60
	v_and_b32_e32 v151, 0xffff0000, v61
	v_lshlrev_b32_e32 v152, 16, v62
	v_lshlrev_b32_e32 v153, 16, v63
	v_and_b32_e32 v154, 0xffff0000, v62
	v_and_b32_e32 v155, 0xffff0000, v63
	v_pk_mul_f32 v[150:151], v[150:151], v[150:151]
	v_pk_mul_f32 v[154:155], v[154:155], v[154:155]
	v_pk_fma_f32 v[148:149], v[148:149], v[148:149], v[150:151]
	v_pk_fma_f32 v[152:153], v[152:153], v[152:153], v[154:155]
	s_nop 0
	v_add_f32_e32 v148, v148, v149
	v_add_f32_e32 v152, v152, v153
	v_add_f32_e32 v159, v148, v152
	s_waitcnt vmcnt(5)
	v_permlane16_swap_b32_e32 v4, v0
	v_permlane16_swap_b32_e32 v5, v1
	v_permlane16_swap_b32_e32 v6, v2
	v_permlane16_swap_b32_e32 v7, v3
	v_mul_f32_e32 v4, 0xbfb8aa3b, v4
	v_mul_f32_e32 v5, 0xbfb8aa3b, v5
	v_mul_f32_e32 v6, 0xbfb8aa3b, v6
	v_mul_f32_e32 v7, 0xbfb8aa3b, v7
	v_mul_f32_e32 v0, 0xbfb8aa3b, v0
	v_mul_f32_e32 v1, 0xbfb8aa3b, v1
	v_mul_f32_e32 v2, 0xbfb8aa3b, v2
	v_mul_f32_e32 v3, 0xbfb8aa3b, v3
	v_exp_f32_e32 v4, v4
	v_exp_f32_e32 v5, v5
	v_exp_f32_e32 v6, v6
	v_exp_f32_e32 v7, v7
	v_exp_f32_e32 v0, v0
	v_exp_f32_e32 v1, v1
	v_exp_f32_e32 v2, v2
	v_exp_f32_e32 v3, v3
	v_add_f32_e32 v4, 1.0, v4
	v_add_f32_e32 v5, 1.0, v5
	v_add_f32_e32 v6, 1.0, v6
	v_add_f32_e32 v7, 1.0, v7
	v_add_f32_e32 v0, 1.0, v0
	v_add_f32_e32 v1, 1.0, v1
	v_add_f32_e32 v2, 1.0, v2
	v_add_f32_e32 v3, 1.0, v3
	v_rcp_f32_e32 v4, v4
	v_rcp_f32_e32 v5, v5
	v_rcp_f32_e32 v6, v6
	v_rcp_f32_e32 v7, v7
	v_rcp_f32_e32 v0, v0
	v_rcp_f32_e32 v1, v1
	v_rcp_f32_e32 v2, v2
	v_rcp_f32_e32 v3, v3
	v_lshlrev_b32_e32 v148, 16, v52
	v_lshlrev_b32_e32 v149, 16, v48
	v_and_b32_e32 v150, 0xffff0000, v52
	v_and_b32_e32 v151, 0xffff0000, v48
	v_fma_f32 v4, v4, v149, v148
	v_fma_f32 v5, v5, v151, v150
	v_lshlrev_b32_e32 v152, 16, v53
	v_lshlrev_b32_e32 v153, 16, v49
	v_and_b32_e32 v154, 0xffff0000, v53
	v_and_b32_e32 v155, 0xffff0000, v49
	v_fma_f32 v6, v6, v153, v152
	v_fma_f32 v7, v7, v155, v154
	v_lshlrev_b32_e32 v148, 16, v54
	v_lshlrev_b32_e32 v149, 16, v50
	v_and_b32_e32 v150, 0xffff0000, v54
	v_and_b32_e32 v151, 0xffff0000, v50
	v_fma_f32 v0, v0, v149, v148
	v_fma_f32 v1, v1, v151, v150
	v_lshlrev_b32_e32 v152, 16, v55
	v_lshlrev_b32_e32 v153, 16, v51
	v_and_b32_e32 v154, 0xffff0000, v55
	v_and_b32_e32 v155, 0xffff0000, v51
	v_fma_f32 v2, v2, v153, v152
	v_fma_f32 v3, v3, v155, v154
	v_cvt_pk_bf16_f32 v52, v4, v5
	v_cvt_pk_bf16_f32 v53, v6, v7
	v_cvt_pk_bf16_f32 v54, v0, v1
	v_cvt_pk_bf16_f32 v55, v2, v3
	s_add_u32 s28, s0, 0x58000
	s_addc_u32 s29, s1, 0
	global_store_dwordx4 v136, v[52:55], s[28:29] offset:256
	v_lshlrev_b32_e32 v148, 16, v52
	v_lshlrev_b32_e32 v149, 16, v53
	v_and_b32_e32 v150, 0xffff0000, v52
	v_and_b32_e32 v151, 0xffff0000, v53
	v_lshlrev_b32_e32 v152, 16, v54
	v_lshlrev_b32_e32 v153, 16, v55
	v_and_b32_e32 v154, 0xffff0000, v54
	v_and_b32_e32 v155, 0xffff0000, v55
	v_pk_mul_f32 v[150:151], v[150:151], v[150:151]
	v_pk_mul_f32 v[154:155], v[154:155], v[154:155]
	v_pk_fma_f32 v[148:149], v[148:149], v[148:149], v[150:151]
	v_pk_fma_f32 v[152:153], v[152:153], v[152:153], v[154:155]
	s_nop 0
	v_add_f32_e32 v148, v148, v149
	v_add_f32_e32 v152, v152, v153
	v_add_f32_e32 v159, v159, v148
	v_add_f32_e32 v159, v159, v152
	ds_bpermute_b32 v148, v137, v156
	ds_bpermute_b32 v149, v137, v157
	ds_bpermute_b32 v150, v137, v158
	ds_bpermute_b32 v151, v137, v159
	s_waitcnt lgkmcnt(0)
	v_add_f32_e32 v156, v156, v148
	v_add_f32_e32 v157, v157, v149
	v_add_f32_e32 v158, v158, v150
	v_add_f32_e32 v159, v159, v151
	ds_bpermute_b32 v148, v138, v156
	ds_bpermute_b32 v149, v138, v157
	ds_bpermute_b32 v150, v138, v158
	ds_bpermute_b32 v151, v138, v159
	s_waitcnt lgkmcnt(0)
	v_add_f32_e32 v156, v156, v148
	v_add_f32_e32 v157, v157, v149
	v_add_f32_e32 v158, v158, v150
	v_add_f32_e32 v159, v159, v151
	s_and_saveexec_b64 vcc, s[4:5]
	ds_write_b32 v146, v156 offset:2048
	ds_write_b32 v146, v157 offset:2304
	ds_write_b32 v146, v158 offset:2560
	ds_write_b32 v146, v159 offset:2816
	s_or_b64 exec, exec, vcc
	v_readlane_b32 s48, v251, 32
	v_readlane_b32 s49, v251, 33
	s_movk_i32 s50, 0x7fff
	s_waitcnt lgkmcnt(0)
	s_barrier
	s_and_saveexec_b64 s[0:1], s[6:7]
	s_cbranch_execz .LBB0_821
	v_add_u32_e32 v0, 0, v142
	v_add_u32_e32 v0, 0x20000, v0
	s_waitcnt lgkmcnt(0)
	ds_read_b128 v[0:3], v0
	s_ashr_i32 s11, s10, 31
	s_waitcnt lgkmcnt(0)
	v_mov_b32_e32 v4, v1
	v_mov_b32_e32 v5, v2
	v_mov_b32_e32 v1, v3
	v_pk_add_f32 v[0:1], v[4:5], v[0:1]
	s_nop 0
	v_add_f32_e32 v2, v0, v1
	v_add_u32_e32 v0, s2, v172
	v_ashrrev_i32_e32 v1, 31, v0
	v_lshl_add_u64 v[0:1], v[0:1], 4, s[14:15]
	v_lshl_add_u64 v[0:1], s[10:11], 2, v[0:1]
	global_store_dword v[0:1], v2, off
